# v5: + adaLN GEMV publishes mod via write-through stores (no per-task L2 write-back), + fused-epilogue row-stat partials loaded in parallel
# speedup vs baseline: 1.0302x; 1.0105x over previous
; #define LAS __attribute__((address_space(3)))
; __device__ __forceinline__ void prologue_phase(const Args& A, LAS unsigned char* lds, int G, const int wv) {
;     ...
;         const float* Wp = A.w_ada + (size_t)l * DM * ADAW + (size_t)(256 * wave) * ADAW + n0 + lane;
;         float a0 = 0.f, a1 = 0.f, a2 = 0.f, a3 = 0.f;
; #pragma unroll 16
;         for (int k = 0; k < 256; ++k) { const float wv = Wp[(size_t)k * ADAW]; const f32x4 ca = *(const LAS f32x4*)(cact + (256 * wave + k) * 4); a0 += ca[0] * wv; a1 += ca[1] * wv; a2 += ca[2] * wv; a3 += ca[3] * wv; }
.LBB0_20:
	v_add_co_u32_e64 v22, s[6:7], s10, v10
	v_add_co_u32_e32 v20, vcc, 0xfffa0000, v10
	s_nop 0
	v_addc_co_u32_e64 v23, s[6:7], 0, v11, s[6:7]
	v_add_co_u32_e64 v24, s[6:7], s13, v10
	v_addc_co_u32_e32 v21, vcc, -1, v11, vcc
	s_nop 0
	v_addc_co_u32_e64 v25, s[6:7], 0, v11, s[6:7]
	v_add_co_u32_e32 v36, vcc, 0xfffac000, v10
	v_add_co_u32_e64 v26, s[6:7], s14, v10
	s_nop 0
	v_addc_co_u32_e32 v37, vcc, -1, v11, vcc
	global_load_dword v16, v[10:11], off nt
	v_addc_co_u32_e64 v27, s[6:7], 0, v11, s[6:7]
	global_load_dword v84, v[22:23], off nt
	global_load_dword v86, v[24:25], off nt
	global_load_dword v88, v[26:27], off nt
	global_load_dword v90, v[20:21], off nt
	v_add_co_u32_e32 v20, vcc, 0xfffb8000, v10
	global_load_dword v92, v[36:37], off nt
	s_nop 0
	v_addc_co_u32_e32 v21, vcc, -1, v11, vcc
	v_add_co_u32_e32 v22, vcc, 0xfffc4000, v10
	global_load_dword v94, v[20:21], off nt
	s_nop 0
	v_addc_co_u32_e32 v23, vcc, -1, v11, vcc
	global_load_dword v96, v[22:23], off nt
	v_add_co_u32_e32 v20, vcc, 0xfffd0000, v10
	v_add_co_u32_e64 v28, s[6:7], s15, v10
	s_nop 0
	v_addc_co_u32_e32 v21, vcc, -1, v11, vcc
	v_add_co_u32_e32 v22, vcc, 0xfffdc000, v10
	global_load_dword v98, v[20:21], off nt
	s_nop 0
	v_addc_co_u32_e32 v23, vcc, -1, v11, vcc
	global_load_dword v100, v[22:23], off nt
	v_add_co_u32_e32 v20, vcc, 0xfffe8000, v10
	v_addc_co_u32_e64 v29, s[6:7], 0, v11, s[6:7]
	s_nop 0
	v_addc_co_u32_e32 v21, vcc, -1, v11, vcc
	global_load_dword v102, v[20:21], off nt
	v_add_co_u32_e64 v30, s[6:7], s16, v10
	v_add_co_u32_e32 v22, vcc, 0xffff4000, v10
	s_nop 0
	v_addc_co_u32_e64 v31, s[6:7], 0, v11, s[6:7]
	v_add_co_u32_e64 v32, s[6:7], s17, v10
	v_addc_co_u32_e32 v23, vcc, -1, v11, vcc
	s_nop 0
	v_addc_co_u32_e64 v33, s[6:7], 0, v11, s[6:7]
	global_load_dword v104, v[22:23], off nt
	global_load_dword v106, v[28:29], off nt
	global_load_dword v108, v[30:31], off nt
	global_load_dword v110, v[32:33], off nt
	v_add_co_u32_e64 v34, s[6:7], s18, v10
	s_add_i32 s24, s12, s21
	s_nop 0
	v_addc_co_u32_e64 v35, s[6:7], 0, v11, s[6:7]
	global_load_dword v112, v[34:35], off nt
	s_add_i32 s6, s24, 0x12000
	s_add_i32 s7, s24, 0x12010
	s_add_i32 s25, s24, 0x12020
	s_add_i32 s26, s24, 0x12030
	s_add_i32 s27, s24, 0x12040
	s_add_i32 s28, s24, 0x12050
	s_add_i32 s29, s24, 0x12060
	s_add_i32 s30, s24, 0x12070
	s_add_i32 s31, s24, 0x12080
	s_add_i32 s33, s24, 0x12090
	s_add_i32 s34, s24, 0x120a0
	s_add_i32 s35, s24, 0x120b0
	s_add_i32 s36, s24, 0x120c0
	s_add_i32 s37, s24, 0x120d0
	s_add_i32 s38, s24, 0x120e0
	s_add_i32 s24, s24, 0x120f0
	v_mov_b32_e32 v19, s6
	v_mov_b32_e32 v24, s7
	v_mov_b32_e32 v28, s25
	v_mov_b32_e32 v32, s26
	v_mov_b32_e32 v36, s27
	v_mov_b32_e32 v40, s28
	v_mov_b32_e32 v44, s29
	v_mov_b32_e32 v48, s30
	v_mov_b32_e32 v52, s31
	v_mov_b32_e32 v56, s33
	v_mov_b32_e32 v60, s34
	v_mov_b32_e32 v64, s35
	v_mov_b32_e32 v68, s36
	v_mov_b32_e32 v72, s37
	v_mov_b32_e32 v76, s38
	v_mov_b32_e32 v80, s24
	ds_read_b128 v[20:23], v19
	ds_read_b128 v[24:27], v24
	ds_read_b128 v[28:31], v28
	ds_read_b128 v[32:35], v32
	ds_read_b128 v[36:39], v36
	ds_read_b128 v[40:43], v40
	ds_read_b128 v[44:47], v44
	ds_read_b128 v[48:51], v48
	ds_read_b128 v[52:55], v52
	ds_read_b128 v[56:59], v56
	ds_read_b128 v[60:63], v60
	ds_read_b128 v[64:67], v64
	ds_read_b128 v[68:71], v68
	ds_read_b128 v[72:75], v72
	ds_read_b128 v[76:79], v76
	ds_read_b128 v[80:83], v80
	s_waitcnt vmcnt(11) lgkmcnt(14)
	v_pk_fma_f32 v[12:13], v[90:91], v[20:21], v[12:13] op_sel_hi:[0,1,1]
	v_pk_fma_f32 v[14:15], v[90:91], v[22:23], v[14:15] op_sel_hi:[0,1,1]
	s_waitcnt vmcnt(10)
	v_pk_fma_f32 v[12:13], v[92:93], v[24:25], v[12:13] op_sel_hi:[0,1,1]
	v_pk_fma_f32 v[14:15], v[92:93], v[26:27], v[14:15] op_sel_hi:[0,1,1]
	s_addk_i32 s21, 0x100
	s_waitcnt vmcnt(9) lgkmcnt(13)
	v_pk_fma_f32 v[12:13], v[94:95], v[28:29], v[12:13] op_sel_hi:[0,1,1]
	v_pk_fma_f32 v[14:15], v[94:95], v[30:31], v[14:15] op_sel_hi:[0,1,1]
	s_cmp_eq_u32 s21, 0
	s_waitcnt vmcnt(8) lgkmcnt(12)
	v_pk_fma_f32 v[12:13], v[96:97], v[32:33], v[12:13] op_sel_hi:[0,1,1]
	v_pk_fma_f32 v[14:15], v[96:97], v[34:35], v[14:15] op_sel_hi:[0,1,1]
	v_lshl_add_u64 v[10:11], v[10:11], 0, s[2:3]
	s_waitcnt vmcnt(7) lgkmcnt(11)
	v_pk_fma_f32 v[12:13], v[98:99], v[36:37], v[12:13] op_sel_hi:[0,1,1]
	v_pk_fma_f32 v[14:15], v[98:99], v[38:39], v[14:15] op_sel_hi:[0,1,1]
	s_waitcnt vmcnt(6) lgkmcnt(10)
	v_pk_fma_f32 v[12:13], v[100:101], v[40:41], v[12:13] op_sel_hi:[0,1,1]
	v_pk_fma_f32 v[14:15], v[100:101], v[42:43], v[14:15] op_sel_hi:[0,1,1]
	s_waitcnt vmcnt(5) lgkmcnt(9)
	v_pk_fma_f32 v[12:13], v[102:103], v[44:45], v[12:13] op_sel_hi:[0,1,1]
	v_pk_fma_f32 v[14:15], v[102:103], v[46:47], v[14:15] op_sel_hi:[0,1,1]
	s_waitcnt vmcnt(4) lgkmcnt(8)
	v_pk_fma_f32 v[12:13], v[104:105], v[48:49], v[12:13] op_sel_hi:[0,1,1]
	v_pk_fma_f32 v[14:15], v[104:105], v[50:51], v[14:15] op_sel_hi:[0,1,1]
	s_waitcnt lgkmcnt(7)
	v_pk_fma_f32 v[12:13], v[16:17], v[52:53], v[12:13] op_sel_hi:[0,1,1]
	v_pk_fma_f32 v[14:15], v[16:17], v[54:55], v[14:15] op_sel_hi:[0,1,1]
	s_waitcnt lgkmcnt(6)
	v_pk_fma_f32 v[12:13], v[84:85], v[56:57], v[12:13] op_sel_hi:[0,1,1]
	v_pk_fma_f32 v[14:15], v[84:85], v[58:59], v[14:15] op_sel_hi:[0,1,1]
	s_waitcnt lgkmcnt(5)
	v_pk_fma_f32 v[12:13], v[86:87], v[60:61], v[12:13] op_sel_hi:[0,1,1]
	v_pk_fma_f32 v[14:15], v[86:87], v[62:63], v[14:15] op_sel_hi:[0,1,1]
	s_waitcnt lgkmcnt(4)
	v_pk_fma_f32 v[12:13], v[88:89], v[64:65], v[12:13] op_sel_hi:[0,1,1]
	v_pk_fma_f32 v[14:15], v[88:89], v[66:67], v[14:15] op_sel_hi:[0,1,1]
	s_waitcnt vmcnt(3) lgkmcnt(3)
	v_pk_fma_f32 v[12:13], v[106:107], v[68:69], v[12:13] op_sel_hi:[0,1,1]
	v_pk_fma_f32 v[14:15], v[106:107], v[70:71], v[14:15] op_sel_hi:[0,1,1]
	s_waitcnt vmcnt(2) lgkmcnt(2)
	v_pk_fma_f32 v[12:13], v[108:109], v[72:73], v[12:13] op_sel_hi:[0,1,1]
	v_pk_fma_f32 v[14:15], v[108:109], v[74:75], v[14:15] op_sel_hi:[0,1,1]
	s_waitcnt vmcnt(1) lgkmcnt(1)
	v_pk_fma_f32 v[12:13], v[110:111], v[76:77], v[12:13] op_sel_hi:[0,1,1]
	v_pk_fma_f32 v[14:15], v[110:111], v[78:79], v[14:15] op_sel_hi:[0,1,1]
	s_waitcnt vmcnt(0) lgkmcnt(0)
	v_pk_fma_f32 v[12:13], v[112:113], v[80:81], v[12:13] op_sel_hi:[0,1,1]
	v_pk_fma_f32 v[14:15], v[112:113], v[82:83], v[14:15] op_sel_hi:[0,1,1]
	s_cbranch_scc0 .LBB0_20
; __device__ __forceinline__ void prologue_phase(const Args& A, LAS unsigned char* lds, int G, const int wv) {
;     ...
;         red[(wave * 4 + 0) * 64 + lane] = a0; red[(wave * 4 + 1) * 64 + lane] = a1; red[(wave * 4 + 2) * 64 + lane] = a2; red[(wave * 4 + 3) * 64 + lane] = a3;
;         __syncthreads();
;         if (tid < 256) { const int bb = tid >> 6; float s = 0.f;
; #pragma unroll
;             for (int w = 0; w < 8; ++w) s += red[(w * 4 + bb) * 64 + lane];
;             mod[(size_t)(l * 4 + bb) * ADAW + n0 + lane] = s + A.b_ada[l * ADAW + n0 + lane]; }
;         __syncthreads();
;         if (tid == 0) { __builtin_amdgcn_fence(__ATOMIC_RELEASE, "agent"); asm volatile("s_waitcnt vmcnt(0)" ::: "memory");
;                         __hip_atomic_fetch_add((unsigned*)(ws + WS_CTL) + 4, 1u, __ATOMIC_RELAXED, __HIP_MEMORY_SCOPE_AGENT); }
	v_add_u32_e32 v10, s11, v3
	ds_write2st64_b32 v10, v12, v13 offset1:1
	ds_write2st64_b32 v10, v14, v15 offset0:2 offset1:3
	s_waitcnt lgkmcnt(0)
	s_barrier
	s_and_saveexec_b64 s[6:7], s[0:1]
	s_cbranch_execz .LBB0_23
	s_mul_i32 s21, s20, 0x3000
	s_add_i32 s21, s21, s8
	v_or_b32_e32 v10, s21, v4
	v_ashrrev_i32_e32 v11, 31, v10
	v_lshl_add_u64 v[10:11], v[10:11], 2, s[46:47]
	global_load_dword v16, v[10:11], off nt
	ds_read2st64_b32 v[10:11], v5 offset1:4
	ds_read2st64_b32 v[12:13], v5 offset0:8 offset1:12
	ds_read2st64_b32 v[14:15], v5 offset0:16 offset1:20
	ds_read2st64_b32 v[20:21], v5 offset0:24 offset1:28
	v_lshl_add_u32 v19, s20, 2, v18
	s_waitcnt lgkmcnt(3)
	v_add_f32_e32 v10, 0, v10
	v_add_f32_e32 v10, v10, v11
	s_waitcnt lgkmcnt(2)
	v_add_f32_e32 v10, v10, v12
	v_readlane_b32 s20, v251, 21
	v_add_f32_e32 v10, v10, v13
	v_readlane_b32 s21, v251, 22
	s_waitcnt lgkmcnt(1)
	v_add_f32_e32 v10, v10, v14
	v_add_f32_e32 v10, v10, v15
	v_mov_b64_e32 v[22:23], s[20:21]
	v_mad_i64_i32 v[22:23], s[20:21], v19, s10, v[22:23]
	s_waitcnt lgkmcnt(0)
	v_add_f32_e32 v10, v10, v20
	v_lshl_add_u64 v[22:23], s[8:9], 2, v[22:23]
	v_add_f32_e32 v10, v10, v21
	s_waitcnt vmcnt(0)
	v_add_f32_e32 v12, v10, v16
	v_lshl_add_u64 v[10:11], v[22:23], 0, v[6:7]
	global_store_dword v[10:11], v12, off sc1
.LBB0_23:
	s_or_b64 exec, exec, s[6:7]
	s_waitcnt vmcnt(0)
	s_barrier
	s_and_saveexec_b64 s[6:7], s[4:5]
	s_cbranch_execz .LBB0_18
	s_mov_b64 s[8:9], exec
	v_mbcnt_lo_u32_b32 v10, s8, 0
	s_waitcnt vmcnt(0)
	s_waitcnt vmcnt(0)
	v_mbcnt_hi_u32_b32 v10, s9, v10
	v_cmp_eq_u32_e32 vcc, 0, v10
	s_and_b64 s[20:21], exec, vcc
	s_mov_b64 exec, s[20:21]
	s_cbranch_execz .LBB0_18
	s_bcnt1_i32_b64 s8, s[8:9]
	v_mov_b32_e32 v10, s8
	global_atomic_add v7, v10, s[60:61] offset:16
	s_branch .LBB0_18

;     __device__ __forceinline__ void fused(f32x4 (&acc)[2][2][4][2], const Unit& u, int wr, int wc, int fr, int fq, LAS unsigned char* lds, int wid, int lane) const {
;     ...
;         if (lane < 32) {
;             const float* slot = xbuf + (size_t)(u.pm * 256 + row) * 8; float t = 0.f;
; #pragma unroll
;             for (int k = 0; k < 8; ++k) t += __hip_atomic_load(slot + k, __ATOMIC_RELAXED, __HIP_MEMORY_SCOPE_AGENT);
;             S[row] = 1.0f / sqrtf(t * (1.0f / DM) + EPS);
;         }
.LBB0_813:
	s_waitcnt vmcnt(0) lgkmcnt(0)
	s_barrier
	s_and_saveexec_b64 s[2:3], s[6:7]
	s_cbranch_execz .LBB0_815
	v_lshlrev_b64 v[130:131], 5, v[130:131]
	v_lshl_add_u64 v[130:131], s[14:15], 0, v[130:131]
	global_load_dword v134, v[130:131], off sc1
	global_load_dword v135, v[130:131], off offset:4 sc1
	global_load_dword v136, v[130:131], off offset:8 sc1
	global_load_dword v137, v[130:131], off offset:12 sc1
	global_load_dword v138, v[130:131], off offset:16 sc1
	global_load_dword v139, v[130:131], off offset:20 sc1
	global_load_dword v140, v[130:131], off offset:24 sc1
	global_load_dword v141, v[130:131], off offset:28 sc1
	s_waitcnt vmcnt(0)
	v_add_f32_e32 v133, 0, v134
	v_add_f32_e32 v133, v133, v135
	v_add_f32_e32 v133, v133, v136
	v_add_f32_e32 v133, v133, v137
	v_add_f32_e32 v133, v133, v138
	v_add_f32_e32 v133, v133, v139
	v_add_f32_e32 v133, v133, v140
	v_add_f32_e32 v130, v133, v141
	v_fmamk_f32 v130, v130, 0x3a000000, v241
	v_cmp_gt_f32_e32 vcc, s85, v130
	v_mul_f32_e32 v131, 0x4f800000, v130
	s_nop 0
	v_cndmask_b32_e32 v130, v130, v131, vcc
	v_sqrt_f32_e32 v131, v130
	s_nop 0
	v_add_u32_e32 v133, -1, v131
	v_fma_f32 v134, -v133, v131, v130
	v_cmp_ge_f32_e64 s[6:7], 0, v134
	v_add_u32_e32 v134, 1, v131
	s_nop 0
	v_cndmask_b32_e64 v133, v131, v133, s[6:7]
	v_fma_f32 v131, -v134, v131, v130
	v_cmp_lt_f32_e64 s[6:7], 0, v131
	s_nop 1
	v_cndmask_b32_e64 v131, v133, v134, s[6:7]
	v_mul_f32_e32 v133, 0x37800000, v131
	v_cndmask_b32_e32 v131, v131, v133, vcc
	v_cmp_class_f32_e32 vcc, v130, v242
	s_nop 1
	v_cndmask_b32_e32 v130, v131, v130, vcc
	v_div_scale_f32 v131, s[6:7], v130, v130, 1.0
	v_rcp_f32_e32 v133, v131
	s_nop 0
	v_fma_f32 v134, -v131, v133, 1.0
	v_fmac_f32_e32 v133, v134, v133
	v_div_scale_f32 v134, vcc, 1.0, v130, 1.0
	v_mul_f32_e32 v135, v134, v133
	v_fma_f32 v136, -v131, v135, v134
	v_fmac_f32_e32 v135, v136, v133
	v_fma_f32 v131, -v131, v135, v134
	v_div_fmas_f32 v131, v131, v133, v135
	v_div_fixup_f32 v130, v131, v130, 1.0
	v_lshl_add_u32 v131, v132, 2, 0
	ds_write_b32 v131, v130 offset:4096

;     __device__ __forceinline__ void fused(f32x4 (&acc)[2][2][4][2], const Unit& u, int wr, int wc, int fr, int fq, LAS unsigned char* lds, int wid, int lane) const {
;     ...
;         if (lane < 32) {
;             const float* slot = xbuf + (size_t)(u.pm * 256 + row) * 8; float t = 0.f;
; #pragma unroll
;             for (int k = 0; k < 8; ++k) t += __hip_atomic_load(slot + k, __ATOMIC_RELAXED, __HIP_MEMORY_SCOPE_AGENT);
;             S[row] = 1.0f / sqrtf(t * (1.0f / DM) + EPS);
;         }
.LBB0_1102:
	s_waitcnt vmcnt(0) lgkmcnt(0)
	s_barrier
	s_and_saveexec_b64 s[2:3], s[6:7]
	s_cbranch_execz .LBB0_1104
	v_lshlrev_b64 v[130:131], 5, v[130:131]
	v_lshl_add_u64 v[130:131], s[14:15], 0, v[130:131]
	global_load_dword v134, v[130:131], off sc1
	global_load_dword v135, v[130:131], off offset:4 sc1
	global_load_dword v136, v[130:131], off offset:8 sc1
	global_load_dword v137, v[130:131], off offset:12 sc1
	global_load_dword v138, v[130:131], off offset:16 sc1
	global_load_dword v139, v[130:131], off offset:20 sc1
	global_load_dword v140, v[130:131], off offset:24 sc1
	global_load_dword v141, v[130:131], off offset:28 sc1
	s_waitcnt vmcnt(0)
	v_add_f32_e32 v132, 0, v134
	v_add_f32_e32 v132, v132, v135
	v_add_f32_e32 v132, v132, v136
	v_add_f32_e32 v132, v132, v137
	v_add_f32_e32 v132, v132, v138
	v_add_f32_e32 v132, v132, v139
	v_add_f32_e32 v132, v132, v140
	v_add_f32_e32 v130, v132, v141
	v_fmamk_f32 v130, v130, 0x3a000000, v241
	v_cmp_gt_f32_e32 vcc, s85, v130
	v_mul_f32_e32 v131, 0x4f800000, v130
	s_nop 0
	v_cndmask_b32_e32 v130, v130, v131, vcc
	v_sqrt_f32_e32 v131, v130
	s_nop 0
	v_add_u32_e32 v132, -1, v131
	v_fma_f32 v134, -v132, v131, v130
	v_cmp_ge_f32_e64 s[6:7], 0, v134
	v_add_u32_e32 v134, 1, v131
	s_nop 0
	v_cndmask_b32_e64 v132, v131, v132, s[6:7]
	v_fma_f32 v131, -v134, v131, v130
	v_cmp_lt_f32_e64 s[6:7], 0, v131
	s_nop 1
	v_cndmask_b32_e64 v131, v132, v134, s[6:7]
	v_mul_f32_e32 v132, 0x37800000, v131
	v_cndmask_b32_e32 v131, v131, v132, vcc
	v_cmp_class_f32_e32 vcc, v130, v242
	s_nop 1
	v_cndmask_b32_e32 v130, v131, v130, vcc
	v_div_scale_f32 v131, s[6:7], v130, v130, 1.0
	v_rcp_f32_e32 v132, v131
	s_nop 0
	v_fma_f32 v134, -v131, v132, 1.0
	v_fmac_f32_e32 v132, v134, v132
	v_div_scale_f32 v134, vcc, 1.0, v130, 1.0
	v_mul_f32_e32 v135, v134, v132
	v_fma_f32 v136, -v131, v135, v134
	v_fmac_f32_e32 v135, v136, v132
	v_fma_f32 v131, -v131, v135, v134
	v_div_fmas_f32 v131, v131, v132, v135
	v_div_fixup_f32 v130, v131, v130, 1.0
	v_lshl_add_u32 v131, v133, 2, 0
	ds_write_b32 v131, v130 offset:4096
